# baseline (speedup 1.0000x reference)
; #define SLOAD(i, k0) do { sr_[i].vs0 = *reinterpret_cast<const bf16x8*>(&Vh[(size_t)((k0) + sr) * LDQ + sc]); sr_[i].vs1 = *reinterpret_cast<const bf16x8*>(&Vh[(size_t)((k0) + 32 + sr) * LDQ + sc]); \
;     sr_[i].ks0 = *reinterpret_cast<const bf16x8*>(&Kh[(size_t)((k0) + sr) * LDQ + sc]); sr_[i].ks1 = *reinterpret_cast<const bf16x8*>(&Kh[(size_t)((k0) + 32 + sr) * LDQ + sc]); } while (0)
; #define SWRITE(b, i) do { *(bf16x8*)((char*)V_lds + (b) * SHM_V + vst0) = sr_[i].vs0;          \
;     *(bf16x8*)((char*)V_lds + (b) * SHM_V + vst1) = sr_[i].vs1; int kc = sc * 2;               \
;     *(bf16x8*)((char*)K_lds + (b) * SHM_K + KSWZ(sr, kc)) = sr_[i].ks0;                       \
;     *(bf16x8*)((char*)K_lds + (b) * SHM_K + KSWZ(32 + sr, kc)) = sr_[i].ks1; } while (0)
; __device__ __forceinline__ void sm2_plain(const f32x16& p0, const f32x16& p1, float& ps, bf16x8& pa0, bf16x8& pa1, bf16x8& pa2, bf16x8& pa3) {
;   constexpr bool SAFE = true;
;   unsigned a0, a1, b0, b1; ps = 0.f;
;   SM2_UNIT(0); SM2_UNIT(1); SM2_UNIT(2); SM2_UNIT(3); SM2_UNIT(4); SM2_UNIT(5); SM2_UNIT(6); SM2_UNIT(7);
;   { auto rr = __builtin_amdgcn_permlane32_swap(__float_as_uint(ps), __float_as_uint(ps), false, false);
;     ps = __uint_as_float(rr[0]) + __uint_as_float(rr[1]); }
; }
; template <bool SAFE>
; __device__ __forceinline__ void diff_core(const bf16* __restrict__ Kh, const bf16* __restrict__ Vh, const int NT, const bf16x8* qr, char* lds,
;                                           const int wid, const int lane_unused, f32x16* o, f32x16& lacc, float& l_reg) {
;     ...
;   const int kw0 = KSWZ(sr, sc * 2), kw1 = KSWZ(32 + sr, sc * 2);
;   SLOAD(0, 0); asm volatile("s_waitcnt vmcnt(0)" ::: "memory"); SWRITE(0, 0);
;   SLOAD(0, 64); asm volatile("s_waitcnt vmcnt(0)" ::: "memory"); SWRITE(1, 0); __syncthreads();
;   SLOAD(0, 128);
;   FIXUP(K_lds, true);
;   int bc = 1, bp = 0, bn = 2;
.LBB0_104:
	s_or_b64 exec, exec, s[4:5]
	v_and_b32_e32 v200, 63, v0
	v_lshlrev_b32_e32 v0, 4, v2
	v_and_b32_e32 v0, 0xc0, v0
	v_and_or_b32 v0, v1, 24, v0
	v_and_b32_e32 v2, 32, v4
	v_and_b32_e32 v1, 0x100, v1
	s_waitcnt lgkmcnt(0)
	v_add_u32_e32 v9, s62, v3
	v_or3_b32 v8, v0, v2, v1
	ds_read_b128 v[0:3], v9 offset:192
	ds_read_b128 v[4:7], v9 offset:224
	ds_read_b128 v[50:53], v9 offset:128
	ds_read_b128 v[54:57], v9 offset:160
	v_sub_f32_e32 v16, v16, v48
	v_sub_f32_e32 v17, v17, v48
	v_sub_f32_e32 v18, v18, v48
	v_sub_f32_e32 v19, v19, v48
	v_sub_f32_e32 v20, v20, v48
	v_sub_f32_e32 v21, v21, v48
	v_sub_f32_e32 v22, v22, v48
	v_sub_f32_e32 v23, v23, v48
	v_sub_f32_e32 v24, v24, v48
	v_sub_f32_e32 v25, v25, v48
	v_sub_f32_e32 v26, v26, v48
	v_sub_f32_e32 v27, v27, v48
	v_sub_f32_e32 v28, v28, v48
	v_sub_f32_e32 v29, v29, v48
	v_sub_f32_e32 v30, v30, v48
	v_sub_f32_e32 v31, v31, v48
	v_sub_f32_e32 v32, v32, v48
	v_sub_f32_e32 v33, v33, v48
	v_sub_f32_e32 v34, v34, v48
	v_sub_f32_e32 v35, v35, v48
	v_sub_f32_e32 v36, v36, v48
	v_sub_f32_e32 v37, v37, v48
	v_sub_f32_e32 v38, v38, v48
	v_sub_f32_e32 v39, v39, v48
	v_sub_f32_e32 v40, v40, v48
	v_sub_f32_e32 v41, v41, v48
	v_sub_f32_e32 v42, v42, v48
	v_sub_f32_e32 v43, v43, v48
	v_sub_f32_e32 v44, v44, v48
	v_sub_f32_e32 v45, v45, v48
	v_sub_f32_e32 v46, v46, v48
	v_sub_f32_e32 v47, v47, v48
	v_exp_f32_e32 v16, v16
	v_exp_f32_e32 v17, v17
	v_exp_f32_e32 v18, v18
	v_exp_f32_e32 v19, v19
	v_exp_f32_e32 v20, v20
	v_exp_f32_e32 v21, v21
	v_exp_f32_e32 v22, v22
	v_exp_f32_e32 v23, v23
	v_exp_f32_e32 v24, v24
	v_exp_f32_e32 v25, v25
	v_exp_f32_e32 v26, v26
	v_exp_f32_e32 v27, v27
	v_exp_f32_e32 v28, v28
	v_exp_f32_e32 v29, v29
	v_exp_f32_e32 v30, v30
	v_exp_f32_e32 v31, v31
	v_exp_f32_e32 v32, v32
	v_exp_f32_e32 v33, v33
	v_exp_f32_e32 v34, v34
	v_exp_f32_e32 v35, v35
	v_exp_f32_e32 v36, v36
	v_exp_f32_e32 v37, v37
	v_exp_f32_e32 v38, v38
	v_exp_f32_e32 v39, v39
	v_exp_f32_e32 v40, v40
	v_exp_f32_e32 v41, v41
	v_exp_f32_e32 v42, v42
	v_exp_f32_e32 v43, v43
	v_exp_f32_e32 v44, v44
	v_exp_f32_e32 v45, v45
	v_exp_f32_e32 v46, v46
	v_exp_f32_e32 v47, v47
	s_lshl_b32 s12, s8, 7
	s_cmp_lg_u32 0, -1
	s_cselect_b32 s5, 0, 0
	s_waitcnt lgkmcnt(2)
	v_pk_mul_f32 v[14:15], v[6:7], 0 op_sel_hi:[1,0]
	v_xor_b32_e32 v80, 0x80000000, v48
	v_add_u32_e32 v211, s5, v8
	v_pk_mul_f32 v[10:11], v[2:3], 0 op_sel_hi:[1,0]
	s_waitcnt lgkmcnt(0)
	v_pk_mul_f32 v[6:7], v[56:57], 0 op_sel_hi:[1,0]
	v_pk_mul_f32 v[2:3], v[52:53], 0 op_sel_hi:[1,0]
	v_pk_mul_f32 v[12:13], v[4:5], 0 op_sel_hi:[1,0]
	v_pk_mul_f32 v[8:9], v[0:1], 0 op_sel_hi:[1,0]
	v_pk_mul_f32 v[4:5], v[54:55], 0 op_sel_hi:[1,0]
	v_pk_mul_f32 v[0:1], v[50:51], 0 op_sel_hi:[1,0]
	v_cvt_pk_bf16_f32 v160, v16, v17
	v_cvt_pk_bf16_f32 v161, v18, v19
	v_cvt_pk_bf16_f32 v182, v20, v21
	v_cvt_pk_bf16_f32 v183, v22, v23
	v_cvt_pk_bf16_f32 v170, v24, v25
	v_cvt_pk_bf16_f32 v171, v26, v27
	v_cvt_pk_bf16_f32 v186, v28, v29
	v_cvt_pk_bf16_f32 v187, v30, v31
	v_cvt_pk_bf16_f32 v180, v32, v33
	v_cvt_pk_bf16_f32 v181, v34, v35
	v_cvt_pk_bf16_f32 v178, v36, v37
	v_cvt_pk_bf16_f32 v179, v38, v39
	v_cvt_pk_bf16_f32 v188, v40, v41
	v_cvt_pk_bf16_f32 v189, v42, v43
	v_cvt_pk_bf16_f32 v174, v44, v45
	v_cvt_pk_bf16_f32 v175, v46, v47
	v_mov_b32_e32 v64, 0
	v_mov_b64_e32 v[46:47], v[14:15]
	v_mov_b64_e32 v[62:63], v[14:15]
	v_mov_b64_e32 v[30:31], v[14:15]
	v_mov_b32_e32 v81, v80
	v_mov_b32_e32 v82, v80
	v_mov_b32_e32 v83, v80
	v_mov_b32_e32 v84, v80
	v_mov_b32_e32 v85, v80
	v_mov_b32_e32 v86, v80
	v_mov_b32_e32 v87, v80
	v_mov_b32_e32 v88, v80
	v_mov_b32_e32 v89, v80
	v_mov_b32_e32 v90, v80
	v_mov_b32_e32 v91, v80
	v_mov_b32_e32 v92, v80
	v_mov_b32_e32 v93, v80
	v_mov_b32_e32 v94, v80
	v_mov_b32_e32 v95, v80
	s_mov_b32 s4, 0
	s_mov_b32 s5, 1
	v_lshl_add_u64 v[190:191], s[10:11], 0, v[194:195]
	v_mad_u32_u24 v247, v201, s80, v194
	s_add_i32 s93, s92, -1
	s_mov_b32 s9, 2
	v_mov_b64_e32 v[44:45], v[12:13]
	v_mov_b64_e32 v[42:43], v[10:11]
	v_mov_b64_e32 v[40:41], v[8:9]
	v_mov_b64_e32 v[38:39], v[6:7]
	v_mov_b64_e32 v[36:37], v[4:5]
	v_mov_b64_e32 v[34:35], v[2:3]
	v_mov_b64_e32 v[32:33], v[0:1]
	v_mov_b64_e32 v[60:61], v[12:13]
	v_mov_b64_e32 v[58:59], v[10:11]
	v_mov_b64_e32 v[56:57], v[8:9]
	v_mov_b64_e32 v[54:55], v[6:7]
	v_mov_b64_e32 v[52:53], v[4:5]
	v_mov_b64_e32 v[50:51], v[2:3]
	v_mov_b64_e32 v[48:49], v[0:1]
	v_mov_b64_e32 v[28:29], v[12:13]
	v_mov_b64_e32 v[26:27], v[10:11]
	v_mov_b64_e32 v[24:25], v[8:9]
	v_mov_b64_e32 v[22:23], v[6:7]
	v_mov_b64_e32 v[20:21], v[4:5]
	v_mov_b64_e32 v[18:19], v[2:3]
	v_mov_b64_e32 v[16:17], v[0:1]
	s_mov_b32 s6, 1
	v_mov_b32_e32 v65, v64
	v_mov_b32_e32 v66, v64
	v_mov_b32_e32 v67, v64
	v_mov_b32_e32 v68, v64
	v_mov_b32_e32 v69, v64
	v_mov_b32_e32 v70, v64
	v_mov_b32_e32 v71, v64
	v_mov_b32_e32 v72, v64
	v_mov_b32_e32 v73, v64
	v_mov_b32_e32 v74, v64
	v_mov_b32_e32 v75, v64
	v_mov_b32_e32 v76, v64
	v_mov_b32_e32 v77, v64
	v_mov_b32_e32 v78, v64
	v_mov_b32_e32 v79, v64
	s_lshl_b32 s98, s6, 14
	v_add_u32_e32 v76, s98, v207
	v_add_u32_e32 v77, s98, v208
	ds_read_b128 v[68:71], v76 offset:49152
	ds_read_b128 v[72:75], v76 offset:57344
	s_waitcnt lgkmcnt(0)
	v_mov_b32_e32 v176, v180
	v_mov_b32_e32 v177, v181
	v_mov_b32_e32 v180, v160
	v_mov_b32_e32 v181, v161
	v_mov_b32_e32 v184, v170
	v_mov_b32_e32 v185, v171
	v_mov_b32_e32 v172, v188
	v_mov_b32_e32 v173, v189
	s_getreg_b32 s98, hwreg(HW_REG_HW_ID, 0, 1)
	s_cmp_eq_u32 s98, 0
	s_cbranch_scc1 .LPRIO_A
	s_setprio 1
; template <int KS, bool SAFE> __device__ __forceinline__ void fused_ks(f32x16* o, f32x16& lacc, int vb, const VFrag& cur, VFrag& nxt, f32x16& p0, f32x16& p1, float& ps, ...
;   if constexpr (KS < 3) { vfrag_issue<KS + 1>(nxt, vb); asm volatile("s_waitcnt lgkmcnt(8)" ::: "memory"); }
;   else asm volatile("s_waitcnt lgkmcnt(0)" ::: "memory");
;   const bf16x8 pa = (KS == 0) ? pa0 : (KS == 1) ? pa1 : (KS == 2) ? pa2 : pa3;
;   SBAR();
;   o[0] = MFMA32(pa, PKV(cur.l0, cur.h0), o[0]); SBAR(); sm1_chunk<KS * 4 + 0>(p0, p1); if constexpr (KS > 0) SM2_UNIT(2 * KS - 1); SBAR();
;   o[1] = MFMA32(pa, PKV(cur.l1, cur.h1), o[1]); SBAR(); sm1_chunk<KS * 4 + 1>(p0, p1);
;   if (dow) {
;     if constexpr (KS == 0) { asm volatile("s_waitcnt vmcnt(0)" ::: "memory"); *reinterpret_cast<bf16x8*>(sd.k0) = st.ks0; }
;     else if constexpr (KS == 1) *reinterpret_cast<bf16x8*>(sd.k1) = st.ks1;
;     else if constexpr (KS == 2) *reinterpret_cast<bf16x8*>(sd.v0) = st.vs0;
;     else *reinterpret_cast<bf16x8*>(sd.v1) = st.vs1;
;   }
;   SBAR();
;   o[2] = MFMA32(pa, PKV(cur.l2, cur.h2), o[2]); SBAR(); sm1_chunk<KS * 4 + 2>(p0, p1); SM2_UNIT(2 * KS); SBAR();
;   o[3] = MFMA32(pa, PKV(cur.l3, cur.h3), o[3]); SBAR(); sm1_chunk<KS * 4 + 3>(p0, p1); SBAR();
;   if constexpr (!SAFE) { lacc = MFMA32(pa, ones, lacc); SBAR(); }
; }
; template <bool SAFE> ...
;   bf16x8 kb[8];
; #pragma unroll
;   for (int d0 = 0; d0 < 4; ++d0) { const int cb = (cb0 + d0 * 16 + hi * 8) * 2;
;     kb[2 * d0] = *reinterpret_cast<const bf16x8*>((const char*)Ks + KSWZ(r32, cb));
;     kb[2 * d0 + 1] = *reinterpret_cast<const bf16x8*>((const char*)Ks + KSWZ(32 + r32, cb)); }
;   VFrag fa, fb;
;   vfrag_issue<0>(fa, vb);
;   p0 = MFMA32(kb[0], qr[0], cinit); p1 = MFMA32(kb[1], qr[0], cinit);
; #pragma unroll
;   for (int d0 = 1; d0 < 4; ++d0) { p0 = MFMA32(kb[2 * d0], qr[d0], p0); p1 = MFMA32(kb[2 * d0 + 1], qr[d0], p1); }
;   SBAR();
;   unsigned a0, a1, b0, b1; ps = 0.f;
;   fused_ks<0, SAFE>(o, lacc, vb, fa, fb, p0, p1, ps, a0, a1, b0, b1, pa0, pa1, pa2, pa3, st, sd, dow, ones);
;   fused_ks<1, SAFE>(o, lacc, vb, fb, fa, p0, p1, ps, a0, a1, b0, b1, pa0, pa1, pa2, pa3, st, sd, dow, ones);
;   fused_ks<2, SAFE>(o, lacc, vb, fa, fb, p0, p1, ps, a0, a1, b0, b1, pa0, pa1, pa2, pa3, st, sd, dow, ones);
;   fused_ks<3, SAFE>(o, lacc, vb, fb, fa, p0, p1, ps, a0, a1, b0, b1, pa0, pa1, pa2, pa3, st, sd, dow, ones);
.LPRIO_A:
.LBB0_105:
	ds_read_b128 v[212:215], v77 offset:49152
	ds_read_b128 v[216:219], v77 offset:57344
	s_lshl_b32 s7, s6, 14
	s_add_i32 s66, s7, 0
	s_add_i32 s98, s5, 2
	s_min_i32 s98, s98, s93
	s_mul_i32 s98, s98, 0x60000
	s_add_u32 s98, s10, s98
	s_addc_u32 s99, s11, 0
	s_add_u32 s100, s98, 0x30000
	s_addc_u32 s101, s99, 0
	v_add_u32_e32 v78, s66, v209
	v_mfma_f32_32x32x16_bf16 v[112:127], v[68:71], v[132:135], v[80:95]
	v_add_u32_e32 v160, s66, v210
	v_lshl_add_u32 v194, s4, 14, v211
	s_mov_b32 s8, s9
	s_lshl_b32 s9, s9, 14
	s_add_i32 s9, s9, 0
	v_add_u32_e32 v76, s9, v207
	v_mfma_f32_32x32x16_bf16 v[96:111], v[72:75], v[132:135], v[80:95]
	ds_read_b128 v[68:71], v78 offset:49152
	ds_read_b128 v[72:75], v78 offset:57344
	v_add_u32_e32 v188, s9, v205
	v_add_u32_e32 v161, s9, v203
	v_add_u32_e32 v170, s9, v204
	v_mfma_f32_16x16x32_bf16 v[64:67], v[180:183], v[148:151], v[64:67]
	s_waitcnt lgkmcnt(3)
	v_mfma_f32_32x32x16_bf16 v[112:127], v[212:215], v[136:139], v[112:127]
	ds_read_b128 v[212:215], v160 offset:49152
	s_waitcnt vmcnt(3)
	ds_write_b128 v161, v[166:169] offset:49152
	global_load_dwordx4 v[166:169], v247, s[98:99] offset:1024
	s_waitcnt lgkmcnt(4)
	v_mfma_f32_32x32x16_bf16 v[96:111], v[216:219], v[136:139], v[96:111]
	ds_read_b128 v[216:219], v160 offset:57344
	v_add_u32_e32 v189, s9, v206
	v_add_u32_e32 v77, s9, v208
	v_mfma_f32_16x16x32_bf16 v[64:67], v[184:187], v[148:151], v[64:67]
	s_waitcnt lgkmcnt(4)
	v_mfma_f32_32x32x16_bf16 v[112:127], v[68:71], v[140:143], v[112:127]
	ds_read_b64_tr_b16 v[220:221], v194 offset:0
	ds_read_b64_tr_b16 v[222:223], v194 offset:0x800
	s_waitcnt vmcnt(3)
	ds_write_b128 v170, v[162:165] offset:49152
	global_load_dwordx4 v[162:165], v247, s[100:101] offset:1024
	v_mfma_f32_16x16x32_bf16 v[64:67], v[176:179], v[148:151], v[64:67]
	s_waitcnt lgkmcnt(6)
	v_mfma_f32_32x32x16_bf16 v[96:111], v[72:75], v[140:143], v[96:111]
	v_mfma_f32_16x16x32_bf16 v[64:67], v[172:175], v[148:151], v[64:67]
	s_waitcnt lgkmcnt(5)
	v_mfma_f32_32x32x16_bf16 v[112:127], v[212:215], v[144:147], v[112:127]
	ds_read_b64_tr_b16 v[212:213], v194 offset:0x200
	ds_read_b64_tr_b16 v[214:215], v194 offset:0xa00
	ds_read_b64_tr_b16 v[224:225], v194 offset:0x400
	ds_read_b64_tr_b16 v[226:227], v194 offset:0xc00
	ds_read_b64_tr_b16 v[228:229], v194 offset:0x600
	ds_read_b64_tr_b16 v[230:231], v194 offset:0xe00
	s_waitcnt lgkmcnt(7)
	v_mfma_f32_32x32x16_bf16 v[96:111], v[216:219], v[144:147], v[96:111]
	ds_read_b64_tr_b16 v[216:217], v194 offset:0x1000
	ds_read_b64_tr_b16 v[218:219], v194 offset:0x1800
	ds_read_b64_tr_b16 v[232:233], v194 offset:0x1200
	ds_read_b64_tr_b16 v[234:235], v194 offset:0x1a00
	ds_read_b64_tr_b16 v[236:237], v194 offset:0x1400
	ds_read_b64_tr_b16 v[238:239], v194 offset:0x1c00
	ds_read_b64_tr_b16 v[240:241], v194 offset:0x1600
	ds_read_b64_tr_b16 v[242:243], v194 offset:0x1e00
	s_waitcnt lgkmcnt(8)
	v_mfma_f32_32x32x16_bf16 v[48:63], v[180:183], v[220:223], v[48:63]
	s_nop 0
	v_exp_f32_e32 v112, v112
	v_exp_f32_e32 v113, v113
	v_mfma_f32_32x32x16_bf16 v[32:47], v[180:183], v[212:215], v[32:47]
	v_exp_f32_e32 v114, v114
	v_exp_f32_e32 v115, v115
	v_mfma_f32_32x32x16_bf16 v[0:15], v[180:183], v[224:227], v[0:15]
	v_exp_f32_e32 v171, v116
	v_exp_f32_e32 v220, v117
	v_mfma_f32_32x32x16_bf16 v[16:31], v[180:183], v[228:231], v[16:31]
	v_exp_f32_e32 v221, v118
	v_exp_f32_e32 v222, v119
	v_cvt_pk_bf16_f32 v180, v112, v113
	v_cvt_pk_bf16_f32 v181, v114, v115
	ds_read_b64_tr_b16 v[112:113], v194 offset:0x2000
	ds_read_b64_tr_b16 v[114:115], v194 offset:0x2800
	ds_read_b64_tr_b16 v[116:117], v194 offset:0x2200
	ds_read_b64_tr_b16 v[118:119], v194 offset:0x2a00
	ds_read_b64_tr_b16 v[248:249], v194 offset:0x2400
	ds_read_b64_tr_b16 v[250:251], v194 offset:0x2c00
	ds_read_b64_tr_b16 v[212:213], v194 offset:0x2600
	ds_read_b64_tr_b16 v[214:215], v194 offset:0x2e00
	s_waitcnt lgkmcnt(8)
	v_mfma_f32_32x32x16_bf16 v[48:63], v[184:187], v[216:219], v[48:63]
	v_cvt_pk_bf16_f32 v182, v171, v220
	v_cvt_pk_bf16_f32 v183, v221, v222
	v_exp_f32_e32 v120, v120
	v_exp_f32_e32 v121, v121
	v_mfma_f32_32x32x16_bf16 v[32:47], v[184:187], v[232:235], v[32:47]
	v_exp_f32_e32 v122, v122
	v_exp_f32_e32 v123, v123
	v_mfma_f32_32x32x16_bf16 v[0:15], v[184:187], v[236:239], v[0:15]
	v_exp_f32_e32 v160, v124
	v_exp_f32_e32 v161, v125
	v_mfma_f32_32x32x16_bf16 v[16:31], v[184:187], v[240:243], v[16:31]
	v_exp_f32_e32 v220, v126
	v_exp_f32_e32 v221, v127
	v_cvt_pk_bf16_f32 v184, v120, v121
	v_cvt_pk_bf16_f32 v185, v122, v123
	s_waitcnt lgkmcnt(0)
	s_barrier
	v_mfma_f32_32x32x16_bf16 v[48:63], v[176:179], v[112:115], v[48:63]
	ds_read_b128 v[68:71], v76 offset:49152
	ds_read_b128 v[72:75], v76 offset:57344
	ds_read_b64_tr_b16 v[120:121], v194 offset:0x3000
	ds_read_b64_tr_b16 v[122:123], v194 offset:0x3800
	ds_read_b64_tr_b16 v[124:125], v194 offset:0x3200
	ds_read_b64_tr_b16 v[126:127], v194 offset:0x3a00
	ds_read_b64_tr_b16 v[252:253], v194 offset:0x3400
	ds_read_b64_tr_b16 v[254:255], v194 offset:0x3c00
	ds_read_b64_tr_b16 v[216:217], v194 offset:0x3600
	ds_read_b64_tr_b16 v[218:219], v194 offset:0x3e00
	v_cvt_pk_bf16_f32 v186, v160, v161
	v_cvt_pk_bf16_f32 v187, v220, v221
	v_exp_f32_e32 v96, v96
	v_exp_f32_e32 v97, v97
	v_mfma_f32_32x32x16_bf16 v[32:47], v[176:179], v[116:119], v[32:47]
	v_exp_f32_e32 v98, v98
	v_exp_f32_e32 v99, v99
	s_waitcnt vmcnt(3)
	ds_write_b128 v188, v[156:159]
	global_load_dwordx4 v[156:159], v247, s[98:99] offset:2048
	v_mfma_f32_32x32x16_bf16 v[0:15], v[176:179], v[248:251], v[0:15]
	v_exp_f32_e32 v100, v100
	v_exp_f32_e32 v101, v101
	v_mfma_f32_32x32x16_bf16 v[16:31], v[176:179], v[212:215], v[16:31]
	v_cvt_pk_bf16_f32 v176, v96, v97
	v_cvt_pk_bf16_f32 v177, v98, v99
	v_exp_f32_e32 v96, v102
	v_exp_f32_e32 v97, v103
	s_waitcnt lgkmcnt(0)
	v_mfma_f32_32x32x16_bf16 v[48:63], v[172:175], v[120:123], v[48:63]
	v_cvt_pk_bf16_f32 v178, v100, v101
	v_cvt_pk_bf16_f32 v179, v96, v97
	v_exp_f32_e32 v98, v104
	v_exp_f32_e32 v99, v105
	v_mfma_f32_32x32x16_bf16 v[32:47], v[172:175], v[124:127], v[32:47]
	v_exp_f32_e32 v96, v106
	v_exp_f32_e32 v97, v107
	s_waitcnt vmcnt(3)
	ds_write_b128 v189, v[152:155]
	global_load_dwordx4 v[152:155], v247, s[100:101] offset:2048
	v_mfma_f32_32x32x16_bf16 v[0:15], v[172:175], v[252:255], v[0:15]
	v_exp_f32_e32 v100, v108
	v_exp_f32_e32 v101, v109
	v_mfma_f32_32x32x16_bf16 v[16:31], v[172:175], v[216:219], v[16:31]
	v_cvt_pk_bf16_f32 v172, v98, v99
	v_cvt_pk_bf16_f32 v173, v96, v97
	v_exp_f32_e32 v102, v110
	v_exp_f32_e32 v103, v111
	v_cvt_pk_bf16_f32 v174, v100, v101
	v_cvt_pk_bf16_f32 v175, v102, v103
	s_add_i32 s5, s5, 1
	s_mov_b32 s9, s4
	s_mov_b32 s4, s6
	s_cmp_lg_u32 s92, s5
	s_mov_b32 s6, s8
	s_cbranch_scc1 .LBB0_105
; #define MFMA32(a, b, c) __builtin_amdgcn_mfma_f32_32x32x16_bf16(a, b, c, 0, 0, 0)
; template <bool SAFE>
; __device__ __forceinline__ void diff_core(const bf16* __restrict__ Kh, const bf16* __restrict__ Vh, const int NT, const bf16x8* qr, char* lds,
;                                           const int wid, const int lane_unused, f32x16* o, f32x16& lacc, float& l_reg) {
;     ...
;   pv_d0(o, vb0 + bp * SHM_V, pa0, pa1, pa2, pa3);
;   if constexpr (!SAFE) {
;     lacc = MFMA32(pa0, ones, lacc); lacc = MFMA32(pa1, ones, lacc); lacc = MFMA32(pa2, ones, lacc); lacc = MFMA32(pa3, ones, lacc); }
; __device__ __forceinline__ void diff_attn_item(const bf16* __restrict__ qkv, bf16* __restrict__ mix, const float* __restrict__ dg,
;                                int tok0  , int key0  , int seq, int head, float lam, float oscale, const int W) {
;     ...
;     bool bad = (FORCE_SAFE != 0);
; #pragma unroll
;     for (int r = 0; r < 16; ++r) bad = bad || !(lacc[r] < 1.0e30f);
;     if (lane == 0) flag_l[wid] = __any(bad) ? 1 : 0;
	v_mov_b32_e32 v160, v180
	v_mov_b32_e32 v161, v181
	v_mov_b32_e32 v170, v184
	v_mov_b32_e32 v171, v185
	v_mov_b32_e32 v180, v176
	v_mov_b32_e32 v181, v177
	v_mov_b32_e32 v188, v172
	v_mov_b32_e32 v189, v173
	s_waitcnt vmcnt(0)
	v_add_u32_e32 v168, s7, v211
	ds_read_b64_tr_b16 v[80:81], v168 offset:0
	ds_read_b64_tr_b16 v[82:83], v168 offset:0x800
	ds_read_b64_tr_b16 v[84:85], v168 offset:0x1000
	ds_read_b64_tr_b16 v[86:87], v168 offset:0x1800
	ds_read_b64_tr_b16 v[88:89], v168 offset:0x2000
	ds_read_b64_tr_b16 v[90:91], v168 offset:0x2800
	ds_read_b64_tr_b16 v[92:93], v168 offset:0x3000
	ds_read_b64_tr_b16 v[94:95], v168 offset:0x3800
	s_waitcnt lgkmcnt(0)
	s_waitcnt vmcnt(0)
	v_mov_b32_e32 v162, v182
	v_mov_b32_e32 v163, v183
	v_mov_b32_e32 v172, v186
	v_mov_b32_e32 v173, v187
	v_mov_b32_e32 v182, v178
	v_mov_b32_e32 v183, v179
	v_mov_b32_e32 v190, v174
	v_mov_b32_e32 v191, v175
	ds_read_b64_tr_b16 v[96:97], v168 offset:0x200
	ds_read_b64_tr_b16 v[98:99], v168 offset:0xa00
	ds_read_b64_tr_b16 v[100:101], v168 offset:0x1200
	ds_read_b64_tr_b16 v[102:103], v168 offset:0x1a00
	ds_read_b64_tr_b16 v[104:105], v168 offset:0x2200
	ds_read_b64_tr_b16 v[106:107], v168 offset:0x2a00
	ds_read_b64_tr_b16 v[108:109], v168 offset:0x3200
	ds_read_b64_tr_b16 v[110:111], v168 offset:0x3a00
	s_waitcnt lgkmcnt(0)
	ds_read_b64_tr_b16 v[112:113], v168 offset:0x400
	ds_read_b64_tr_b16 v[114:115], v168 offset:0xc00
	ds_read_b64_tr_b16 v[116:117], v168 offset:0x1400
	ds_read_b64_tr_b16 v[118:119], v168 offset:0x1c00
	ds_read_b64_tr_b16 v[120:121], v168 offset:0x2400
	ds_read_b64_tr_b16 v[122:123], v168 offset:0x2c00
	ds_read_b64_tr_b16 v[124:125], v168 offset:0x3400
	ds_read_b64_tr_b16 v[126:127], v168 offset:0x3c00
	s_waitcnt lgkmcnt(0)
	ds_read_b64_tr_b16 v[152:153], v168 offset:0x600
	ds_read_b64_tr_b16 v[154:155], v168 offset:0xe00
	ds_read_b64_tr_b16 v[156:157], v168 offset:0x1600
	ds_read_b64_tr_b16 v[158:159], v168 offset:0x1e00
	ds_read_b64_tr_b16 v[164:165], v168 offset:0x2600
	ds_read_b64_tr_b16 v[166:167], v168 offset:0x2e00
	ds_read_b64_tr_b16 v[174:175], v168 offset:0x3600
	ds_read_b64_tr_b16 v[176:177], v168 offset:0x3e00
	s_waitcnt lgkmcnt(0)
	v_mfma_f32_16x16x32_bf16 v[64:67], v[160:163], v[148:151], v[64:67]
	v_cmp_eq_u32_e32 vcc, 0, v200
	v_mfma_f32_32x32x16_bf16 v[48:63], v[160:163], v[80:83], v[48:63]
	v_mfma_f32_32x32x16_bf16 v[32:47], v[160:163], v[96:99], v[32:47]
	v_mfma_f32_32x32x16_bf16 v[0:15], v[160:163], v[112:115], v[0:15]
	v_mfma_f32_32x32x16_bf16 v[16:31], v[160:163], v[152:155], v[16:31]
	v_mfma_f32_16x16x32_bf16 v[64:67], v[170:173], v[148:151], v[64:67]
	v_mfma_f32_32x32x16_bf16 v[48:63], v[170:173], v[84:87], v[48:63]
	v_mfma_f32_32x32x16_bf16 v[32:47], v[170:173], v[100:103], v[32:47]
	v_mfma_f32_32x32x16_bf16 v[0:15], v[170:173], v[116:119], v[0:15]
	v_mfma_f32_32x32x16_bf16 v[16:31], v[170:173], v[156:159], v[16:31]
	v_mfma_f32_16x16x32_bf16 v[64:67], v[180:183], v[148:151], v[64:67]
	v_mfma_f32_32x32x16_bf16 v[48:63], v[180:183], v[88:91], v[48:63]
	v_mfma_f32_32x32x16_bf16 v[32:47], v[180:183], v[104:107], v[32:47]
	v_mfma_f32_32x32x16_bf16 v[0:15], v[180:183], v[120:123], v[0:15]
	v_mfma_f32_32x32x16_bf16 v[16:31], v[180:183], v[164:167], v[16:31]
	v_mfma_f32_16x16x32_bf16 v[64:67], v[188:191], v[148:151], v[64:67]
	v_mfma_f32_32x32x16_bf16 v[48:63], v[188:191], v[92:95], v[48:63]
	v_mfma_f32_32x32x16_bf16 v[32:47], v[188:191], v[108:111], v[32:47]
	v_mfma_f32_32x32x16_bf16 v[0:15], v[188:191], v[124:127], v[0:15]
	v_mfma_f32_32x32x16_bf16 v[16:31], v[188:191], v[174:177], v[16:31]
	v_and_b32_e32 v248, 15, v200
	v_lshrrev_b32_e32 v249, 4, v200
	v_and_b32_e32 v250, 1, v200
	v_lshlrev_b32_e32 v249, 4, v249
	v_lshl_add_u32 v249, v250, 6, v249
	v_add_u32_e32 v249, s62, v249
	v_cmp_gt_u32_e64 s[98:99], 2, v248
	v_lshl_add_u32 v250, v198, 4, s62
	s_nop 7
	s_and_saveexec_b64 s[100:101], s[98:99]
	ds_write_b128 v249, v[64:67]
	s_mov_b64 exec, s[100:101]
	s_waitcnt lgkmcnt(0)
	ds_read_b128 v[64:67], v250
	ds_read_b128 v[68:71], v250 offset:32
	ds_read_b128 v[72:75], v250 offset:64
	ds_read_b128 v[76:79], v250 offset:96
	s_waitcnt lgkmcnt(0)
	s_and_saveexec_b64 s[6:7], vcc
	s_cbranch_execz .LBB0_108
	s_nop 5
	v_cmp_ngt_f32_e32 vcc, s85, v64
	v_cmp_ngt_f32_e64 s[4:5], s85, v65
	s_or_b64 s[4:5], vcc, s[4:5]
	v_cmp_ngt_f32_e32 vcc, s85, v66
	s_or_b64 s[4:5], s[4:5], vcc
	v_cmp_ngt_f32_e32 vcc, s85, v67
	s_or_b64 s[4:5], s[4:5], vcc
	v_cmp_ngt_f32_e32 vcc, s85, v68
	s_or_b64 s[4:5], s[4:5], vcc
	v_cmp_ngt_f32_e32 vcc, s85, v69
	s_or_b64 s[4:5], s[4:5], vcc
	v_cmp_ngt_f32_e32 vcc, s85, v70
	s_or_b64 s[4:5], s[4:5], vcc
	v_cmp_ngt_f32_e32 vcc, s85, v71
	s_or_b64 s[4:5], s[4:5], vcc
	v_cmp_ngt_f32_e32 vcc, s85, v72
	s_or_b64 s[4:5], s[4:5], vcc
	v_cmp_ngt_f32_e32 vcc, s85, v73
	s_or_b64 s[4:5], s[4:5], vcc
	v_cmp_ngt_f32_e32 vcc, s85, v74
	s_or_b64 s[4:5], s[4:5], vcc
	v_cmp_ngt_f32_e32 vcc, s85, v75
	s_or_b64 s[4:5], s[4:5], vcc
	v_cmp_ngt_f32_e32 vcc, s85, v76
	s_or_b64 s[4:5], s[4:5], vcc
	v_cmp_ngt_f32_e32 vcc, s85, v77
	s_or_b64 s[4:5], s[4:5], vcc
	v_cmp_ngt_f32_e32 vcc, s85, v78
	s_or_b64 s[4:5], s[4:5], vcc
	v_cmp_ngt_f32_e32 vcc, s85, v79
	s_or_b64 s[4:5], s[4:5], vcc
	v_cndmask_b32_e64 v80, 0, 1, s[4:5]
	v_cmp_ne_u32_e32 vcc, 0, v80
	s_cmp_lg_u64 vcc, 0
	s_cselect_b64 s[4:5], -1, 0
	v_cndmask_b32_e64 v80, 0, 1, s[4:5]
	v_readlane_b32 s4, v246, 17
	s_nop 1
	v_mov_b32_e32 v81, s4
	ds_write_b32 v81, v80

; #define SLOAD(i, k0) do { sr_[i].vs0 = *reinterpret_cast<const bf16x8*>(&Vh[(size_t)((k0) + sr) * LDQ + sc]); sr_[i].vs1 = *reinterpret_cast<const bf16x8*>(&Vh[(size_t)((k0) + 32 + sr) * LDQ + sc]); \
;     sr_[i].ks0 = *reinterpret_cast<const bf16x8*>(&Kh[(size_t)((k0) + sr) * LDQ + sc]); sr_[i].ks1 = *reinterpret_cast<const bf16x8*>(&Kh[(size_t)((k0) + 32 + sr) * LDQ + sc]); } while (0)
; #define SWRITE(b, i) do { *(bf16x8*)((char*)V_lds + (b) * SHM_V + vst0) = sr_[i].vs0;          \
;     *(bf16x8*)((char*)V_lds + (b) * SHM_V + vst1) = sr_[i].vs1; int kc = sc * 2;               \
;     *(bf16x8*)((char*)K_lds + (b) * SHM_K + KSWZ(sr, kc)) = sr_[i].ks0;                       \
;     *(bf16x8*)((char*)K_lds + (b) * SHM_K + KSWZ(32 + sr, kc)) = sr_[i].ks1; } while (0)
; __device__ __forceinline__ void sm2_plain(const f32x16& p0, const f32x16& p1, float& ps, bf16x8& pa0, bf16x8& pa1, bf16x8& pa2, bf16x8& pa3) {
;   constexpr bool SAFE = true;
;   unsigned a0, a1, b0, b1; ps = 0.f;
;   SM2_UNIT(0); SM2_UNIT(1); SM2_UNIT(2); SM2_UNIT(3); SM2_UNIT(4); SM2_UNIT(5); SM2_UNIT(6); SM2_UNIT(7);
;   { auto rr = __builtin_amdgcn_permlane32_swap(__float_as_uint(ps), __float_as_uint(ps), false, false);
;     ps = __uint_as_float(rr[0]) + __uint_as_float(rr[1]); }
; }
; template <bool SAFE>
; __device__ __forceinline__ void diff_core(const bf16* __restrict__ Kh, const bf16* __restrict__ Vh, const int NT, const bf16x8* qr, char* lds,
;                                           const int wid, const int lane_unused, f32x16* o, f32x16& lacc, float& l_reg) {
;     ...
;   const int kw0 = KSWZ(sr, sc * 2), kw1 = KSWZ(32 + sr, sc * 2);
;   SLOAD(0, 0); asm volatile("s_waitcnt vmcnt(0)" ::: "memory"); SWRITE(0, 0);
;   SLOAD(0, 64); asm volatile("s_waitcnt vmcnt(0)" ::: "memory"); SWRITE(1, 0); __syncthreads();
;   SLOAD(0, 128);
;   FIXUP(K_lds, true);
;   int bc = 1, bp = 0, bn = 2;
.LBB0_315:
	s_or_b64 exec, exec, s[6:7]
	v_and_b32_e32 v200, 63, v0
	v_lshlrev_b32_e32 v0, 4, v2
	v_and_b32_e32 v0, 0xc0, v0
	v_and_or_b32 v0, v1, 24, v0
	v_and_b32_e32 v2, 32, v4
	v_and_b32_e32 v1, 0x100, v1
	s_waitcnt lgkmcnt(0)
	v_add_u32_e32 v9, s62, v3
	v_or3_b32 v8, v0, v2, v1
	ds_read_b128 v[0:3], v9 offset:192
	ds_read_b128 v[4:7], v9 offset:224
	ds_read_b128 v[50:53], v9 offset:128
	ds_read_b128 v[54:57], v9 offset:160
	v_sub_f32_e32 v16, v16, v48
	v_sub_f32_e32 v17, v17, v48
	v_sub_f32_e32 v18, v18, v48
	v_sub_f32_e32 v19, v19, v48
	v_sub_f32_e32 v20, v20, v48
	v_sub_f32_e32 v21, v21, v48
	v_sub_f32_e32 v22, v22, v48
	v_sub_f32_e32 v23, v23, v48
	v_sub_f32_e32 v24, v24, v48
	v_sub_f32_e32 v25, v25, v48
	v_sub_f32_e32 v26, v26, v48
	v_sub_f32_e32 v27, v27, v48
	v_sub_f32_e32 v28, v28, v48
	v_sub_f32_e32 v29, v29, v48
	v_sub_f32_e32 v30, v30, v48
	v_sub_f32_e32 v31, v31, v48
	v_sub_f32_e32 v32, v32, v48
	v_sub_f32_e32 v33, v33, v48
	v_sub_f32_e32 v34, v34, v48
	v_sub_f32_e32 v35, v35, v48
	v_sub_f32_e32 v36, v36, v48
	v_sub_f32_e32 v37, v37, v48
	v_sub_f32_e32 v38, v38, v48
	v_sub_f32_e32 v39, v39, v48
	v_sub_f32_e32 v40, v40, v48
	v_sub_f32_e32 v41, v41, v48
	v_sub_f32_e32 v42, v42, v48
	v_sub_f32_e32 v43, v43, v48
	v_sub_f32_e32 v44, v44, v48
	v_sub_f32_e32 v45, v45, v48
	v_sub_f32_e32 v46, v46, v48
	v_sub_f32_e32 v47, v47, v48
	v_exp_f32_e32 v16, v16
	v_exp_f32_e32 v17, v17
	v_exp_f32_e32 v18, v18
	v_exp_f32_e32 v19, v19
	v_exp_f32_e32 v20, v20
	v_exp_f32_e32 v21, v21
	v_exp_f32_e32 v22, v22
	v_exp_f32_e32 v23, v23
	v_exp_f32_e32 v24, v24
	v_exp_f32_e32 v25, v25
	v_exp_f32_e32 v26, v26
	v_exp_f32_e32 v27, v27
	v_exp_f32_e32 v28, v28
	v_exp_f32_e32 v29, v29
	v_exp_f32_e32 v30, v30
	v_exp_f32_e32 v31, v31
	v_exp_f32_e32 v32, v32
	v_exp_f32_e32 v33, v33
	v_exp_f32_e32 v34, v34
	v_exp_f32_e32 v35, v35
	v_exp_f32_e32 v36, v36
	v_exp_f32_e32 v37, v37
	v_exp_f32_e32 v38, v38
	v_exp_f32_e32 v39, v39
	v_exp_f32_e32 v40, v40
	v_exp_f32_e32 v41, v41
	v_exp_f32_e32 v42, v42
	v_exp_f32_e32 v43, v43
	v_exp_f32_e32 v44, v44
	v_exp_f32_e32 v45, v45
	v_exp_f32_e32 v46, v46
	v_exp_f32_e32 v47, v47
	s_lshl_b32 s20, s26, 7
	s_cmp_lg_u32 0, -1
	s_cselect_b32 s7, 0, 0
	s_waitcnt lgkmcnt(2)
	v_pk_mul_f32 v[14:15], v[6:7], 0 op_sel_hi:[1,0]
	v_xor_b32_e32 v80, 0x80000000, v48
	v_add_u32_e32 v211, s7, v8
	v_pk_mul_f32 v[10:11], v[2:3], 0 op_sel_hi:[1,0]
	s_waitcnt lgkmcnt(0)
	v_pk_mul_f32 v[6:7], v[56:57], 0 op_sel_hi:[1,0]
	v_pk_mul_f32 v[2:3], v[52:53], 0 op_sel_hi:[1,0]
	v_pk_mul_f32 v[12:13], v[4:5], 0 op_sel_hi:[1,0]
	v_pk_mul_f32 v[8:9], v[0:1], 0 op_sel_hi:[1,0]
	v_pk_mul_f32 v[4:5], v[54:55], 0 op_sel_hi:[1,0]
	v_pk_mul_f32 v[0:1], v[50:51], 0 op_sel_hi:[1,0]
	v_cvt_pk_bf16_f32 v160, v16, v17
	v_cvt_pk_bf16_f32 v161, v18, v19
	v_cvt_pk_bf16_f32 v182, v20, v21
	v_cvt_pk_bf16_f32 v183, v22, v23
	v_cvt_pk_bf16_f32 v170, v24, v25
	v_cvt_pk_bf16_f32 v171, v26, v27
	v_cvt_pk_bf16_f32 v186, v28, v29
	v_cvt_pk_bf16_f32 v187, v30, v31
	v_cvt_pk_bf16_f32 v180, v32, v33
	v_cvt_pk_bf16_f32 v181, v34, v35
	v_cvt_pk_bf16_f32 v178, v36, v37
	v_cvt_pk_bf16_f32 v179, v38, v39
	v_cvt_pk_bf16_f32 v188, v40, v41
	v_cvt_pk_bf16_f32 v189, v42, v43
	v_cvt_pk_bf16_f32 v174, v44, v45
	v_cvt_pk_bf16_f32 v175, v46, v47
	v_mov_b32_e32 v64, 0
	v_mov_b64_e32 v[46:47], v[14:15]
	v_mov_b64_e32 v[62:63], v[14:15]
	v_mov_b64_e32 v[30:31], v[14:15]
	v_mov_b32_e32 v81, v80
	v_mov_b32_e32 v82, v80
	v_mov_b32_e32 v83, v80
	v_mov_b32_e32 v84, v80
	v_mov_b32_e32 v85, v80
	v_mov_b32_e32 v86, v80
	v_mov_b32_e32 v87, v80
	v_mov_b32_e32 v88, v80
	v_mov_b32_e32 v89, v80
	v_mov_b32_e32 v90, v80
	v_mov_b32_e32 v91, v80
	v_mov_b32_e32 v92, v80
	v_mov_b32_e32 v93, v80
	v_mov_b32_e32 v94, v80
	v_mov_b32_e32 v95, v80
	s_mov_b32 s6, 0
	s_mov_b32 s7, 1
	v_lshl_add_u64 v[190:191], s[14:15], 0, v[194:195]
	v_mad_u32_u24 v247, v201, s41, v194
	s_add_i32 s64, s55, -1
	s_mov_b32 s27, 2
	v_mov_b64_e32 v[44:45], v[12:13]
	v_mov_b64_e32 v[42:43], v[10:11]
	v_mov_b64_e32 v[40:41], v[8:9]
	v_mov_b64_e32 v[38:39], v[6:7]
	v_mov_b64_e32 v[36:37], v[4:5]
	v_mov_b64_e32 v[34:35], v[2:3]
	v_mov_b64_e32 v[32:33], v[0:1]
	v_mov_b64_e32 v[60:61], v[12:13]
	v_mov_b64_e32 v[58:59], v[10:11]
	v_mov_b64_e32 v[56:57], v[8:9]
	v_mov_b64_e32 v[54:55], v[6:7]
	v_mov_b64_e32 v[52:53], v[4:5]
	v_mov_b64_e32 v[50:51], v[2:3]
	v_mov_b64_e32 v[48:49], v[0:1]
	v_mov_b64_e32 v[28:29], v[12:13]
	v_mov_b64_e32 v[26:27], v[10:11]
	v_mov_b64_e32 v[24:25], v[8:9]
	v_mov_b64_e32 v[22:23], v[6:7]
	v_mov_b64_e32 v[20:21], v[4:5]
	v_mov_b64_e32 v[18:19], v[2:3]
	v_mov_b64_e32 v[16:17], v[0:1]
	s_mov_b32 s10, 1
	v_mov_b32_e32 v65, v64
	v_mov_b32_e32 v66, v64
	v_mov_b32_e32 v67, v64
	v_mov_b32_e32 v68, v64
	v_mov_b32_e32 v69, v64
	v_mov_b32_e32 v70, v64
	v_mov_b32_e32 v71, v64
	v_mov_b32_e32 v72, v64
	v_mov_b32_e32 v73, v64
	v_mov_b32_e32 v74, v64
	v_mov_b32_e32 v75, v64
	v_mov_b32_e32 v76, v64
	v_mov_b32_e32 v77, v64
	v_mov_b32_e32 v78, v64
	v_mov_b32_e32 v79, v64
	s_lshl_b32 s98, s10, 14
	v_add_u32_e32 v76, s98, v207
	v_add_u32_e32 v77, s98, v208
	ds_read_b128 v[68:71], v76 offset:49152
	ds_read_b128 v[72:75], v76 offset:57344
	s_waitcnt lgkmcnt(0)
	v_mov_b32_e32 v176, v180
	v_mov_b32_e32 v177, v181
	v_mov_b32_e32 v180, v160
	v_mov_b32_e32 v181, v161
	v_mov_b32_e32 v184, v170
	v_mov_b32_e32 v185, v171
	v_mov_b32_e32 v172, v188
	v_mov_b32_e32 v173, v189
	s_getreg_b32 s98, hwreg(HW_REG_HW_ID, 0, 1)
	s_cmp_eq_u32 s98, 0
	s_cbranch_scc1 .LPRIO_B
	s_setprio 1
; template <int KS, bool SAFE> __device__ __forceinline__ void fused_ks(f32x16* o, f32x16& lacc, int vb, const VFrag& cur, VFrag& nxt, f32x16& p0, f32x16& p1, float& ps, ...
;   if constexpr (KS < 3) { vfrag_issue<KS + 1>(nxt, vb); asm volatile("s_waitcnt lgkmcnt(8)" ::: "memory"); }
;   else asm volatile("s_waitcnt lgkmcnt(0)" ::: "memory");
;   const bf16x8 pa = (KS == 0) ? pa0 : (KS == 1) ? pa1 : (KS == 2) ? pa2 : pa3;
;   SBAR();
;   o[0] = MFMA32(pa, PKV(cur.l0, cur.h0), o[0]); SBAR(); sm1_chunk<KS * 4 + 0>(p0, p1); if constexpr (KS > 0) SM2_UNIT(2 * KS - 1); SBAR();
;   o[1] = MFMA32(pa, PKV(cur.l1, cur.h1), o[1]); SBAR(); sm1_chunk<KS * 4 + 1>(p0, p1);
;   if (dow) {
;     if constexpr (KS == 0) { asm volatile("s_waitcnt vmcnt(0)" ::: "memory"); *reinterpret_cast<bf16x8*>(sd.k0) = st.ks0; }
;     else if constexpr (KS == 1) *reinterpret_cast<bf16x8*>(sd.k1) = st.ks1;
;     else if constexpr (KS == 2) *reinterpret_cast<bf16x8*>(sd.v0) = st.vs0;
;     else *reinterpret_cast<bf16x8*>(sd.v1) = st.vs1;
;   }
;   SBAR();
;   o[2] = MFMA32(pa, PKV(cur.l2, cur.h2), o[2]); SBAR(); sm1_chunk<KS * 4 + 2>(p0, p1); SM2_UNIT(2 * KS); SBAR();
;   o[3] = MFMA32(pa, PKV(cur.l3, cur.h3), o[3]); SBAR(); sm1_chunk<KS * 4 + 3>(p0, p1); SBAR();
;   if constexpr (!SAFE) { lacc = MFMA32(pa, ones, lacc); SBAR(); }
; }
; template <bool SAFE> ...
;   bf16x8 kb[8];
; #pragma unroll
;   for (int d0 = 0; d0 < 4; ++d0) { const int cb = (cb0 + d0 * 16 + hi * 8) * 2;
;     kb[2 * d0] = *reinterpret_cast<const bf16x8*>((const char*)Ks + KSWZ(r32, cb));
;     kb[2 * d0 + 1] = *reinterpret_cast<const bf16x8*>((const char*)Ks + KSWZ(32 + r32, cb)); }
;   VFrag fa, fb;
;   vfrag_issue<0>(fa, vb);
;   p0 = MFMA32(kb[0], qr[0], cinit); p1 = MFMA32(kb[1], qr[0], cinit);
; #pragma unroll
;   for (int d0 = 1; d0 < 4; ++d0) { p0 = MFMA32(kb[2 * d0], qr[d0], p0); p1 = MFMA32(kb[2 * d0 + 1], qr[d0], p1); }
;   SBAR();
;   unsigned a0, a1, b0, b1; ps = 0.f;
;   fused_ks<0, SAFE>(o, lacc, vb, fa, fb, p0, p1, ps, a0, a1, b0, b1, pa0, pa1, pa2, pa3, st, sd, dow, ones);
;   fused_ks<1, SAFE>(o, lacc, vb, fb, fa, p0, p1, ps, a0, a1, b0, b1, pa0, pa1, pa2, pa3, st, sd, dow, ones);
;   fused_ks<2, SAFE>(o, lacc, vb, fa, fb, p0, p1, ps, a0, a1, b0, b1, pa0, pa1, pa2, pa3, st, sd, dow, ones);
;   fused_ks<3, SAFE>(o, lacc, vb, fb, fa, p0, p1, ps, a0, a1, b0, b1, pa0, pa1, pa2, pa3, st, sd, dow, ones);
.LPRIO_B:
.LBB0_316:
	ds_read_b128 v[212:215], v77 offset:49152
	ds_read_b128 v[216:219], v77 offset:57344
	s_lshl_b32 s11, s10, 14
	s_add_i32 s8, s11, 0
	s_add_i32 s98, s7, 2
	s_min_i32 s98, s98, s64
	s_mul_i32 s98, s98, 0x60000
	s_add_u32 s98, s14, s98
	s_addc_u32 s99, s15, 0
	s_add_u32 s100, s98, 0x30000
	s_addc_u32 s101, s99, 0
	v_add_u32_e32 v78, s8, v209
	v_mfma_f32_32x32x16_bf16 v[112:127], v[68:71], v[132:135], v[80:95]
	v_add_u32_e32 v160, s8, v210
	v_lshl_add_u32 v194, s6, 14, v211
	s_lshl_b32 s9, s27, 14
	s_add_i32 s9, s9, 0
	s_mov_b32 s26, s27
	v_add_u32_e32 v76, s9, v207
	v_mfma_f32_32x32x16_bf16 v[96:111], v[72:75], v[132:135], v[80:95]
	ds_read_b128 v[68:71], v78 offset:49152
	ds_read_b128 v[72:75], v78 offset:57344
	v_add_u32_e32 v188, s9, v205
	v_add_u32_e32 v161, s9, v203
	v_add_u32_e32 v170, s9, v204
	v_mfma_f32_16x16x32_bf16 v[64:67], v[180:183], v[148:151], v[64:67]
	s_waitcnt lgkmcnt(3)
	v_mfma_f32_32x32x16_bf16 v[112:127], v[212:215], v[136:139], v[112:127]
	ds_read_b128 v[212:215], v160 offset:49152
	s_waitcnt vmcnt(3)
	ds_write_b128 v161, v[166:169] offset:49152
	global_load_dwordx4 v[166:169], v247, s[98:99] offset:1024
	s_waitcnt lgkmcnt(4)
	v_mfma_f32_32x32x16_bf16 v[96:111], v[216:219], v[136:139], v[96:111]
	ds_read_b128 v[216:219], v160 offset:57344
	v_add_u32_e32 v189, s9, v206
	v_add_u32_e32 v77, s9, v208
	v_mfma_f32_16x16x32_bf16 v[64:67], v[184:187], v[148:151], v[64:67]
	s_waitcnt lgkmcnt(4)
	v_mfma_f32_32x32x16_bf16 v[112:127], v[68:71], v[140:143], v[112:127]
	ds_read_b64_tr_b16 v[220:221], v194 offset:0
	ds_read_b64_tr_b16 v[222:223], v194 offset:0x800
	s_waitcnt vmcnt(3)
	ds_write_b128 v170, v[162:165] offset:49152
	global_load_dwordx4 v[162:165], v247, s[100:101] offset:1024
	v_mfma_f32_16x16x32_bf16 v[64:67], v[176:179], v[148:151], v[64:67]
	s_waitcnt lgkmcnt(6)
	v_mfma_f32_32x32x16_bf16 v[96:111], v[72:75], v[140:143], v[96:111]
	v_mfma_f32_16x16x32_bf16 v[64:67], v[172:175], v[148:151], v[64:67]
	s_waitcnt lgkmcnt(5)
	v_mfma_f32_32x32x16_bf16 v[112:127], v[212:215], v[144:147], v[112:127]
	ds_read_b64_tr_b16 v[212:213], v194 offset:0x200
	ds_read_b64_tr_b16 v[214:215], v194 offset:0xa00
	ds_read_b64_tr_b16 v[224:225], v194 offset:0x400
	ds_read_b64_tr_b16 v[226:227], v194 offset:0xc00
	ds_read_b64_tr_b16 v[228:229], v194 offset:0x600
	ds_read_b64_tr_b16 v[230:231], v194 offset:0xe00
	s_waitcnt lgkmcnt(7)
	v_mfma_f32_32x32x16_bf16 v[96:111], v[216:219], v[144:147], v[96:111]
	ds_read_b64_tr_b16 v[216:217], v194 offset:0x1000
	ds_read_b64_tr_b16 v[218:219], v194 offset:0x1800
	ds_read_b64_tr_b16 v[232:233], v194 offset:0x1200
	ds_read_b64_tr_b16 v[234:235], v194 offset:0x1a00
	ds_read_b64_tr_b16 v[236:237], v194 offset:0x1400
	ds_read_b64_tr_b16 v[238:239], v194 offset:0x1c00
	ds_read_b64_tr_b16 v[240:241], v194 offset:0x1600
	ds_read_b64_tr_b16 v[242:243], v194 offset:0x1e00
	s_waitcnt lgkmcnt(8)
	v_mfma_f32_32x32x16_bf16 v[48:63], v[180:183], v[220:223], v[48:63]
	s_nop 0
	v_exp_f32_e32 v112, v112
	v_exp_f32_e32 v113, v113
	v_mfma_f32_32x32x16_bf16 v[32:47], v[180:183], v[212:215], v[32:47]
	v_exp_f32_e32 v114, v114
	v_exp_f32_e32 v115, v115
	v_mfma_f32_32x32x16_bf16 v[0:15], v[180:183], v[224:227], v[0:15]
	v_exp_f32_e32 v171, v116
	v_exp_f32_e32 v220, v117
	v_mfma_f32_32x32x16_bf16 v[16:31], v[180:183], v[228:231], v[16:31]
	v_exp_f32_e32 v221, v118
	v_exp_f32_e32 v222, v119
	v_cvt_pk_bf16_f32 v180, v112, v113
	v_cvt_pk_bf16_f32 v181, v114, v115
	ds_read_b64_tr_b16 v[112:113], v194 offset:0x2000
	ds_read_b64_tr_b16 v[114:115], v194 offset:0x2800
	ds_read_b64_tr_b16 v[116:117], v194 offset:0x2200
	ds_read_b64_tr_b16 v[118:119], v194 offset:0x2a00
	ds_read_b64_tr_b16 v[248:249], v194 offset:0x2400
	ds_read_b64_tr_b16 v[250:251], v194 offset:0x2c00
	ds_read_b64_tr_b16 v[212:213], v194 offset:0x2600
	ds_read_b64_tr_b16 v[214:215], v194 offset:0x2e00
	s_waitcnt lgkmcnt(8)
	v_mfma_f32_32x32x16_bf16 v[48:63], v[184:187], v[216:219], v[48:63]
	v_cvt_pk_bf16_f32 v182, v171, v220
	v_cvt_pk_bf16_f32 v183, v221, v222
	v_exp_f32_e32 v120, v120
	v_exp_f32_e32 v121, v121
	v_mfma_f32_32x32x16_bf16 v[32:47], v[184:187], v[232:235], v[32:47]
	v_exp_f32_e32 v122, v122
	v_exp_f32_e32 v123, v123
	v_mfma_f32_32x32x16_bf16 v[0:15], v[184:187], v[236:239], v[0:15]
	v_exp_f32_e32 v160, v124
	v_exp_f32_e32 v161, v125
	v_mfma_f32_32x32x16_bf16 v[16:31], v[184:187], v[240:243], v[16:31]
	v_exp_f32_e32 v220, v126
	v_exp_f32_e32 v221, v127
	v_cvt_pk_bf16_f32 v184, v120, v121
	v_cvt_pk_bf16_f32 v185, v122, v123
	s_waitcnt lgkmcnt(0)
	s_barrier
	v_mfma_f32_32x32x16_bf16 v[48:63], v[176:179], v[112:115], v[48:63]
	ds_read_b128 v[68:71], v76 offset:49152
	ds_read_b128 v[72:75], v76 offset:57344
	ds_read_b64_tr_b16 v[120:121], v194 offset:0x3000
	ds_read_b64_tr_b16 v[122:123], v194 offset:0x3800
	ds_read_b64_tr_b16 v[124:125], v194 offset:0x3200
	ds_read_b64_tr_b16 v[126:127], v194 offset:0x3a00
	ds_read_b64_tr_b16 v[252:253], v194 offset:0x3400
	ds_read_b64_tr_b16 v[254:255], v194 offset:0x3c00
	ds_read_b64_tr_b16 v[216:217], v194 offset:0x3600
	ds_read_b64_tr_b16 v[218:219], v194 offset:0x3e00
	v_cvt_pk_bf16_f32 v186, v160, v161
	v_cvt_pk_bf16_f32 v187, v220, v221
	v_exp_f32_e32 v96, v96
	v_exp_f32_e32 v97, v97
	v_mfma_f32_32x32x16_bf16 v[32:47], v[176:179], v[116:119], v[32:47]
	v_exp_f32_e32 v98, v98
	v_exp_f32_e32 v99, v99
	s_waitcnt vmcnt(3)
	ds_write_b128 v188, v[156:159]
	global_load_dwordx4 v[156:159], v247, s[98:99] offset:2048
	v_mfma_f32_32x32x16_bf16 v[0:15], v[176:179], v[248:251], v[0:15]
	v_exp_f32_e32 v100, v100
	v_exp_f32_e32 v101, v101
	v_mfma_f32_32x32x16_bf16 v[16:31], v[176:179], v[212:215], v[16:31]
	v_cvt_pk_bf16_f32 v176, v96, v97
	v_cvt_pk_bf16_f32 v177, v98, v99
	v_exp_f32_e32 v96, v102
	v_exp_f32_e32 v97, v103
	s_waitcnt lgkmcnt(0)
	v_mfma_f32_32x32x16_bf16 v[48:63], v[172:175], v[120:123], v[48:63]
	v_cvt_pk_bf16_f32 v178, v100, v101
	v_cvt_pk_bf16_f32 v179, v96, v97
	v_exp_f32_e32 v98, v104
	v_exp_f32_e32 v99, v105
	v_mfma_f32_32x32x16_bf16 v[32:47], v[172:175], v[124:127], v[32:47]
	v_exp_f32_e32 v96, v106
	v_exp_f32_e32 v97, v107
	s_waitcnt vmcnt(3)
	ds_write_b128 v189, v[152:155]
	global_load_dwordx4 v[152:155], v247, s[100:101] offset:2048
	v_mfma_f32_32x32x16_bf16 v[0:15], v[172:175], v[252:255], v[0:15]
	v_exp_f32_e32 v100, v108
	v_exp_f32_e32 v101, v109
	v_mfma_f32_32x32x16_bf16 v[16:31], v[172:175], v[216:219], v[16:31]
	v_cvt_pk_bf16_f32 v172, v98, v99
	v_cvt_pk_bf16_f32 v173, v96, v97
	v_exp_f32_e32 v102, v110
	v_exp_f32_e32 v103, v111
	v_cvt_pk_bf16_f32 v174, v100, v101
	v_cvt_pk_bf16_f32 v175, v102, v103
	s_add_i32 s7, s7, 1
	s_mov_b32 s27, s6
	s_mov_b32 s6, s10
	s_cmp_lg_u32 s55, s7
	s_mov_b32 s10, s26
	s_cbranch_scc1 .LBB0_316
; #define MFMA32(a, b, c) __builtin_amdgcn_mfma_f32_32x32x16_bf16(a, b, c, 0, 0, 0)
; template <bool SAFE>
; __device__ __forceinline__ void diff_core(const bf16* __restrict__ Kh, const bf16* __restrict__ Vh, const int NT, const bf16x8* qr, char* lds,
;                                           const int wid, const int lane_unused, f32x16* o, f32x16& lacc, float& l_reg) {
;     ...
;   pv_d0(o, vb0 + bp * SHM_V, pa0, pa1, pa2, pa3);
;   if constexpr (!SAFE) {
;     lacc = MFMA32(pa0, ones, lacc); lacc = MFMA32(pa1, ones, lacc); lacc = MFMA32(pa2, ones, lacc); lacc = MFMA32(pa3, ones, lacc); }
; __device__ __forceinline__ void diff_attn_item(const bf16* __restrict__ qkv, bf16* __restrict__ mix, const float* __restrict__ dg,
;                                int tok0  , int key0  , int seq, int head, float lam, float oscale, const int W) {
;     ...
;     bool bad = (FORCE_SAFE != 0);
; #pragma unroll
;     for (int r = 0; r < 16; ++r) bad = bad || !(lacc[r] < 1.0e30f);
;     if (lane == 0) flag_l[wid] = __any(bad) ? 1 : 0;
	v_mov_b32_e32 v160, v180
	v_mov_b32_e32 v161, v181
	v_mov_b32_e32 v170, v184
	v_mov_b32_e32 v171, v185
	v_mov_b32_e32 v180, v176
	v_mov_b32_e32 v181, v177
	v_mov_b32_e32 v188, v172
	v_mov_b32_e32 v189, v173
	s_waitcnt vmcnt(0)
	v_add_u32_e32 v168, s11, v211
	ds_read_b64_tr_b16 v[80:81], v168 offset:0
	ds_read_b64_tr_b16 v[82:83], v168 offset:0x800
	ds_read_b64_tr_b16 v[84:85], v168 offset:0x1000
	ds_read_b64_tr_b16 v[86:87], v168 offset:0x1800
	ds_read_b64_tr_b16 v[88:89], v168 offset:0x2000
	ds_read_b64_tr_b16 v[90:91], v168 offset:0x2800
	ds_read_b64_tr_b16 v[92:93], v168 offset:0x3000
	ds_read_b64_tr_b16 v[94:95], v168 offset:0x3800
	s_waitcnt lgkmcnt(0)
	s_waitcnt vmcnt(0)
	v_mov_b32_e32 v162, v182
	v_mov_b32_e32 v163, v183
	v_mov_b32_e32 v172, v186
	v_mov_b32_e32 v173, v187
	v_mov_b32_e32 v182, v178
	v_mov_b32_e32 v183, v179
	v_mov_b32_e32 v190, v174
	v_mov_b32_e32 v191, v175
	ds_read_b64_tr_b16 v[96:97], v168 offset:0x200
	ds_read_b64_tr_b16 v[98:99], v168 offset:0xa00
	ds_read_b64_tr_b16 v[100:101], v168 offset:0x1200
	ds_read_b64_tr_b16 v[102:103], v168 offset:0x1a00
	ds_read_b64_tr_b16 v[104:105], v168 offset:0x2200
	ds_read_b64_tr_b16 v[106:107], v168 offset:0x2a00
	ds_read_b64_tr_b16 v[108:109], v168 offset:0x3200
	ds_read_b64_tr_b16 v[110:111], v168 offset:0x3a00
	s_waitcnt lgkmcnt(0)
	ds_read_b64_tr_b16 v[112:113], v168 offset:0x400
	ds_read_b64_tr_b16 v[114:115], v168 offset:0xc00
	ds_read_b64_tr_b16 v[116:117], v168 offset:0x1400
	ds_read_b64_tr_b16 v[118:119], v168 offset:0x1c00
	ds_read_b64_tr_b16 v[120:121], v168 offset:0x2400
	ds_read_b64_tr_b16 v[122:123], v168 offset:0x2c00
	ds_read_b64_tr_b16 v[124:125], v168 offset:0x3400
	ds_read_b64_tr_b16 v[126:127], v168 offset:0x3c00
	s_waitcnt lgkmcnt(0)
	ds_read_b64_tr_b16 v[152:153], v168 offset:0x600
	ds_read_b64_tr_b16 v[154:155], v168 offset:0xe00
	ds_read_b64_tr_b16 v[156:157], v168 offset:0x1600
	ds_read_b64_tr_b16 v[158:159], v168 offset:0x1e00
	ds_read_b64_tr_b16 v[164:165], v168 offset:0x2600
	ds_read_b64_tr_b16 v[166:167], v168 offset:0x2e00
	ds_read_b64_tr_b16 v[174:175], v168 offset:0x3600
	ds_read_b64_tr_b16 v[176:177], v168 offset:0x3e00
	s_waitcnt lgkmcnt(0)
	v_mfma_f32_16x16x32_bf16 v[64:67], v[160:163], v[148:151], v[64:67]
	v_cmp_eq_u32_e32 vcc, 0, v200
	v_mfma_f32_32x32x16_bf16 v[48:63], v[160:163], v[80:83], v[48:63]
	v_mfma_f32_32x32x16_bf16 v[32:47], v[160:163], v[96:99], v[32:47]
	v_mfma_f32_32x32x16_bf16 v[0:15], v[160:163], v[112:115], v[0:15]
	v_mfma_f32_32x32x16_bf16 v[16:31], v[160:163], v[152:155], v[16:31]
	v_mfma_f32_16x16x32_bf16 v[64:67], v[170:173], v[148:151], v[64:67]
	v_mfma_f32_32x32x16_bf16 v[48:63], v[170:173], v[84:87], v[48:63]
	v_mfma_f32_32x32x16_bf16 v[32:47], v[170:173], v[100:103], v[32:47]
	v_mfma_f32_32x32x16_bf16 v[0:15], v[170:173], v[116:119], v[0:15]
	v_mfma_f32_32x32x16_bf16 v[16:31], v[170:173], v[156:159], v[16:31]
	v_mfma_f32_16x16x32_bf16 v[64:67], v[180:183], v[148:151], v[64:67]
	v_mfma_f32_32x32x16_bf16 v[48:63], v[180:183], v[88:91], v[48:63]
	v_mfma_f32_32x32x16_bf16 v[32:47], v[180:183], v[104:107], v[32:47]
	v_mfma_f32_32x32x16_bf16 v[0:15], v[180:183], v[120:123], v[0:15]
	v_mfma_f32_32x32x16_bf16 v[16:31], v[180:183], v[164:167], v[16:31]
	v_mfma_f32_16x16x32_bf16 v[64:67], v[188:191], v[148:151], v[64:67]
	v_mfma_f32_32x32x16_bf16 v[48:63], v[188:191], v[92:95], v[48:63]
	v_mfma_f32_32x32x16_bf16 v[32:47], v[188:191], v[108:111], v[32:47]
	v_mfma_f32_32x32x16_bf16 v[0:15], v[188:191], v[124:127], v[0:15]
	v_mfma_f32_32x32x16_bf16 v[16:31], v[188:191], v[174:177], v[16:31]
	v_and_b32_e32 v248, 15, v200
	v_lshrrev_b32_e32 v249, 4, v200
	v_and_b32_e32 v250, 1, v200
	v_lshlrev_b32_e32 v249, 4, v249
	v_lshl_add_u32 v249, v250, 6, v249
	v_add_u32_e32 v249, s62, v249
	v_cmp_gt_u32_e64 s[98:99], 2, v248
	v_lshl_add_u32 v250, v198, 4, s62
	s_nop 7
	s_and_saveexec_b64 s[100:101], s[98:99]
	ds_write_b128 v249, v[64:67]
	s_mov_b64 exec, s[100:101]
	s_waitcnt lgkmcnt(0)
	ds_read_b128 v[64:67], v250
	ds_read_b128 v[68:71], v250 offset:32
	ds_read_b128 v[72:75], v250 offset:64
	ds_read_b128 v[76:79], v250 offset:96
	s_waitcnt lgkmcnt(0)
	s_and_saveexec_b64 s[10:11], vcc
	s_cbranch_execz .LBB0_319
	s_nop 5
	v_cmp_ngt_f32_e32 vcc, s44, v64
	v_cmp_ngt_f32_e64 s[6:7], s44, v65
	s_or_b64 s[6:7], vcc, s[6:7]
	v_cmp_ngt_f32_e32 vcc, s44, v66
	s_or_b64 s[6:7], s[6:7], vcc
	v_cmp_ngt_f32_e32 vcc, s44, v67
	s_or_b64 s[6:7], s[6:7], vcc
	v_cmp_ngt_f32_e32 vcc, s44, v68
	s_or_b64 s[6:7], s[6:7], vcc
	v_cmp_ngt_f32_e32 vcc, s44, v69
	s_or_b64 s[6:7], s[6:7], vcc
	v_cmp_ngt_f32_e32 vcc, s44, v70
	s_or_b64 s[6:7], s[6:7], vcc
	v_cmp_ngt_f32_e32 vcc, s44, v71
	s_or_b64 s[6:7], s[6:7], vcc
	v_cmp_ngt_f32_e32 vcc, s44, v72
	s_or_b64 s[6:7], s[6:7], vcc
	v_cmp_ngt_f32_e32 vcc, s44, v73
	s_or_b64 s[6:7], s[6:7], vcc
	v_cmp_ngt_f32_e32 vcc, s44, v74
	s_or_b64 s[6:7], s[6:7], vcc
	v_cmp_ngt_f32_e32 vcc, s44, v75
	s_or_b64 s[6:7], s[6:7], vcc
	v_cmp_ngt_f32_e32 vcc, s44, v76
	s_or_b64 s[6:7], s[6:7], vcc
	v_cmp_ngt_f32_e32 vcc, s44, v77
	s_or_b64 s[6:7], s[6:7], vcc
	v_cmp_ngt_f32_e32 vcc, s44, v78
	s_or_b64 s[6:7], s[6:7], vcc
	v_cmp_ngt_f32_e32 vcc, s44, v79
	s_or_b64 s[6:7], s[6:7], vcc
	v_cndmask_b32_e64 v80, 0, 1, s[6:7]
	v_cmp_ne_u32_e32 vcc, 0, v80
	s_cmp_lg_u64 vcc, 0
	s_cselect_b64 s[6:7], -1, 0
	v_cndmask_b32_e64 v80, 0, 1, s[6:7]
	v_readlane_b32 s6, v246, 17
	s_nop 1
	v_mov_b32_e32 v81, s6
	ds_write_b32 v81, v80
